# first-barrier census: 16 counter loads issued together instead of serially
# baseline (speedup 1.0000x reference)
; __device__ __forceinline__ unsigned xb_ld(unsigned* p)              { return __hip_atomic_load(p, __ATOMIC_RELAXED, __HIP_MEMORY_SCOPE_AGENT); }
; __device__ __forceinline__ void xcd_barrier_complete(unsigned* bar, unsigned x, unsigned& nloc, unsigned& nx) {
;     ...
;     for (;;) {
;         sum = 0u; cnt = 0u; mine = 0u;
; #pragma unroll
;         for (unsigned j = 0; j < 16; ++j) { const unsigned c = xb_ld(&bar[XB_XCNT(j)]); sum += c; cnt += (c > 0u) ? 1u : 0u; mine = (j == x) ? c : mine; }
;         if (sum == G) break;
.LBB0_1964:
	v_mov_b64_e32 v[16:17], s[2:3]
	flat_load_dword v1, v[16:17] offset:1024 sc1
	flat_load_dword v0, v[16:17] offset:1280 sc1
	flat_load_dword v2, v[16:17] offset:1536 sc1
	flat_load_dword v3, v[16:17] offset:1792 sc1
	flat_load_dword v4, v[16:17] offset:2048 sc1
	flat_load_dword v5, v[16:17] offset:2304 sc1
	flat_load_dword v6, v[16:17] offset:2560 sc1
	flat_load_dword v7, v[16:17] offset:2816 sc1
	flat_load_dword v8, v[16:17] offset:3072 sc1
	flat_load_dword v9, v[16:17] offset:3328 sc1
	flat_load_dword v10, v[16:17] offset:3584 sc1
	flat_load_dword v11, v[16:17] offset:3840 sc1
	v_mov_b64_e32 v[16:17], s[4:5]
	flat_load_dword v12, v[16:17] sc1
	v_mov_b64_e32 v[16:17], s[6:7]
	flat_load_dword v13, v[16:17] sc1
	v_mov_b64_e32 v[16:17], s[8:9]
	flat_load_dword v14, v[16:17] sc1
	v_mov_b64_e32 v[16:17], s[10:11]
	flat_load_dword v15, v[16:17] sc1
	s_or_b64 s[18:19], s[18:19], exec
	s_or_b64 s[16:17], s[16:17], exec
	s_waitcnt vmcnt(0) lgkmcnt(0)
	v_add_u32_e32 v16, v0, v1
	v_add_u32_e32 v16, v16, v2
	v_add_u32_e32 v16, v16, v3
	v_add_u32_e32 v16, v16, v4
	v_add_u32_e32 v16, v16, v5
	v_add_u32_e32 v16, v16, v6
	v_add_u32_e32 v16, v16, v7
	v_add_u32_e32 v16, v16, v8
	v_add_u32_e32 v16, v16, v9
	v_add_u32_e32 v16, v16, v10
	v_add_u32_e32 v16, v16, v11
	v_add_u32_e32 v16, v16, v12
	v_add_u32_e32 v16, v16, v13
	v_add_u32_e32 v16, v16, v14
	v_add_u32_e32 v16, v16, v15
	v_cmp_ne_u32_e32 vcc, s92, v16
	s_and_saveexec_b64 s[20:21], vcc
	s_cbranch_execz .LBB0_1963
	s_and_b32 s24, s30, 0xff
	s_mov_b64 s[22:23], -1
	s_cmp_eq_u32 s24, 0
	s_mov_b64 s[26:27], -1
	s_mov_b64 s[24:25], -1
	s_sleep 1
	s_cbranch_scc1 .LBB0_1967
	s_and_saveexec_b64 s[28:29], s[26:27]
	s_cbranch_execz .LBB0_1962
	s_branch .LBB0_1970
